# A-mixer band tiles: wave-uniform skip of the causal mask block when nothing / everything is masked (on top of P3 residual preload + B mask dispatch)
# speedup vs baseline: 1.0001x; 1.0001x over previous
; __device__ __forceinline__ void cmask(f32x16&p0,f32x16&p1,int jb,int qrel,int hi){
;   const float NEG=-INFINITY; int d=qrel-64*jb-4*hi; asm volatile("":"+v"(d));
;   #pragma unroll
;   for(int r=0;r<16;++r){const int off=(r&3)+8*(r>>2); if(d<off)p0[r]=NEG; if(d<off+32)p1[r]=NEG;}
; }
.LBB0_284:
	s_add_u32 s68, s30, s0
	s_addc_u32 s69, s76, s1
	s_add_u32 s2, s68, 0xb020000
	s_addc_u32 s3, s69, 0
	s_lshl_b32 s96, s92, 1
	s_add_i32 s4, s96, s87
	s_mov_b32 s5, m0
	s_mov_b32 m0, s4
	s_nop 0
	global_load_lds_dwordx4 v223, s[2:3]
	s_mov_b32 m0, s5
	s_add_u32 s2, s68, 0xb020080
	s_addc_u32 s3, s69, 0
	s_addk_i32 s4, 0x2000
	s_mov_b32 s5, m0
	s_mov_b32 m0, s4
	s_nop 0
	global_load_lds_dwordx4 v223, s[2:3]
	s_mov_b32 m0, s5
	s_add_i32 s80, s95, s31
	s_add_i32 s2, s80, -2
	s_cmp_lt_i32 s2, 0
	v_add_u32_e32 v225, s94, v67
	s_cbranch_scc1 .LBB0_286
	v_readfirstlane_b32 s100, v225
	s_nop 3
	s_cmp_ge_i32 s100, 63
	s_cbranch_scc1 .LBB0_286
	s_cmp_le_i32 s100, -32
	s_cbranch_scc1 .Lcm_empty_a
	v_mov_b32_e32 v88, v225
	s_nop 0
	v_cmp_gt_i32_e64 s[62:63], 26, v88
	v_cmp_gt_i32_e64 s[64:65], 27, v88
	v_cmp_gt_i32_e64 s[60:61], 25, v88
	s_and_b64 s[62:63], s[64:65], s[62:63]
	v_cmp_gt_i32_e64 s[58:59], 24, v88
	s_and_b64 s[60:61], s[62:63], s[60:61]
	v_cmp_gt_i32_e64 s[56:57], 19, v88
	s_and_b64 s[58:59], s[60:61], s[58:59]
	v_cmp_gt_i32_e64 s[54:55], 18, v88
	s_and_b64 s[56:57], s[58:59], s[56:57]
	v_cmp_gt_i32_e64 s[52:53], 17, v88
	s_and_b64 s[54:55], s[56:57], s[54:55]
	v_cmp_gt_i32_e64 s[50:51], 16, v88
	s_and_b64 s[52:53], s[54:55], s[52:53]
	v_cmp_gt_i32_e64 s[48:49], 11, v88
	s_and_b64 s[50:51], s[52:53], s[50:51]
	v_cmp_gt_i32_e64 s[46:47], 10, v88
	s_and_b64 s[48:49], s[50:51], s[48:49]
	v_cmp_gt_i32_e64 s[44:45], 9, v88
	s_and_b64 s[46:47], s[48:49], s[46:47]
	v_cmp_gt_i32_e64 s[42:43], 8, v88
	s_and_b64 s[44:45], s[46:47], s[44:45]
	v_cmp_gt_i32_e64 s[40:41], 3, v88
	s_and_b64 s[42:43], s[44:45], s[42:43]
	v_cmp_gt_i32_e64 s[38:39], 2, v88
	s_and_b64 s[40:41], s[42:43], s[40:41]
	v_cmp_gt_i32_e64 s[36:37], 1, v88
	s_and_b64 s[38:39], s[40:41], s[38:39]
	v_cmp_gt_i32_e64 s[34:35], 0, v88
	s_and_b64 s[36:37], s[38:39], s[36:37]
	s_and_b64 s[34:35], s[36:37], s[34:35]
	v_cmp_gt_i32_e64 s[28:29], 58, v88
	v_cndmask_b32_e64 v130, v130, v248, s[34:35]
	v_cmp_gt_i32_e64 s[34:35], 59, v88
	v_cmp_gt_i32_e64 s[26:27], 57, v88
	s_and_b64 s[28:29], s[34:35], s[28:29]
	v_cmp_gt_i32_e64 s[24:25], 56, v88
	s_and_b64 s[26:27], s[28:29], s[26:27]
	v_cmp_gt_i32_e64 s[22:23], 51, v88
	s_and_b64 s[24:25], s[26:27], s[24:25]
	v_cmp_gt_i32_e64 s[20:21], 50, v88
	s_and_b64 s[22:23], s[24:25], s[22:23]
	v_cmp_gt_i32_e64 s[18:19], 49, v88
	s_and_b64 s[20:21], s[22:23], s[20:21]
	v_cmp_gt_i32_e64 s[16:17], 48, v88
	s_and_b64 s[18:19], s[20:21], s[18:19]
	v_cmp_gt_i32_e64 s[14:15], 43, v88
	s_and_b64 s[16:17], s[18:19], s[16:17]
	v_cmp_gt_i32_e64 s[12:13], 42, v88
	s_and_b64 s[14:15], s[16:17], s[14:15]
	v_cmp_gt_i32_e64 s[10:11], 41, v88
	s_and_b64 s[12:13], s[14:15], s[12:13]
	v_cmp_gt_i32_e64 s[8:9], 40, v88
	s_and_b64 s[10:11], s[12:13], s[10:11]
	v_cmp_gt_i32_e64 s[6:7], 35, v88
	s_and_b64 s[8:9], s[10:11], s[8:9]
	v_cmp_gt_i32_e64 s[4:5], 34, v88
	s_and_b64 s[6:7], s[8:9], s[6:7]
	v_cmp_gt_i32_e64 s[2:3], 33, v88
	s_and_b64 s[4:5], s[6:7], s[4:5]
	v_cmp_gt_i32_e32 vcc, 32, v88
	s_and_b64 s[2:3], s[4:5], s[2:3]
	s_and_b64 vcc, s[2:3], vcc
	v_cndmask_b32_e64 v145, v145, v248, s[64:65]
	v_cndmask_b32_e64 v144, v144, v248, s[62:63]
	v_cndmask_b32_e64 v143, v143, v248, s[60:61]
	v_cndmask_b32_e64 v142, v142, v248, s[58:59]
	v_cndmask_b32_e64 v141, v141, v248, s[56:57]
	v_cndmask_b32_e64 v140, v140, v248, s[54:55]
	v_cndmask_b32_e64 v139, v139, v248, s[52:53]
	v_cndmask_b32_e64 v138, v138, v248, s[50:51]
	v_cndmask_b32_e64 v137, v137, v248, s[48:49]
	v_cndmask_b32_e64 v136, v136, v248, s[46:47]
	v_cndmask_b32_e64 v135, v135, v248, s[44:45]
	v_cndmask_b32_e64 v134, v134, v248, s[42:43]
	v_cndmask_b32_e64 v133, v133, v248, s[40:41]
	v_cndmask_b32_e64 v132, v132, v248, s[38:39]
	v_cndmask_b32_e64 v131, v131, v248, s[36:37]
	v_cndmask_b32_e64 v129, v129, v248, s[34:35]
	v_cndmask_b32_e64 v128, v128, v248, s[28:29]
	v_cndmask_b32_e64 v127, v127, v248, s[26:27]
	v_cndmask_b32_e64 v126, v126, v248, s[24:25]
	v_cndmask_b32_e64 v125, v125, v248, s[22:23]
	v_cndmask_b32_e64 v124, v124, v248, s[20:21]
	v_cndmask_b32_e64 v123, v123, v248, s[18:19]
	v_cndmask_b32_e64 v122, v122, v248, s[16:17]
	v_cndmask_b32_e64 v121, v121, v248, s[14:15]
	v_cndmask_b32_e64 v120, v120, v248, s[12:13]
	v_cndmask_b32_e64 v119, v119, v248, s[10:11]
	v_cndmask_b32_e64 v118, v118, v248, s[8:9]
	v_cndmask_b32_e64 v117, v117, v248, s[6:7]
	v_cndmask_b32_e64 v116, v116, v248, s[4:5]
	v_cndmask_b32_e64 v115, v115, v248, s[2:3]
	v_cndmask_b32_e32 v114, v114, v248, vcc

; __device__ __forceinline__ void cmask(f32x16&p0,f32x16&p1,int jb,int qrel,int hi){
;   const float NEG=-INFINITY; int d=qrel-64*jb-4*hi; asm volatile("":"+v"(d));
;   #pragma unroll
;   for(int r=0;r<16;++r){const int off=(r&3)+8*(r>>2); if(d<off)p0[r]=NEG; if(d<off+32)p1[r]=NEG;}
; }
.LBB0_298:
	s_add_i32 s80, s80, -1
	s_cmp_lt_i32 s80, 0
	s_cbranch_scc1 .LBB0_300
	v_readfirstlane_b32 s100, v225
	s_nop 3
	s_add_i32 s100, s100, -64
	s_cmp_ge_i32 s100, 63
	s_cbranch_scc1 .LBB0_300
	s_cmp_le_i32 s100, -32
	s_cbranch_scc1 .Lcm_empty_b
	v_subrev_u32_e32 v114, 64, v225
	s_nop 0
	v_cmp_gt_i32_e64 s[62:63], 26, v114
	v_cmp_gt_i32_e64 s[64:65], 27, v114
	v_cmp_gt_i32_e64 s[60:61], 25, v114
	s_and_b64 s[62:63], s[64:65], s[62:63]
	v_cmp_gt_i32_e64 s[58:59], 24, v114
	s_and_b64 s[60:61], s[62:63], s[60:61]
	v_cmp_gt_i32_e64 s[56:57], 19, v114
	s_and_b64 s[58:59], s[60:61], s[58:59]
	v_cmp_gt_i32_e64 s[54:55], 18, v114
	s_and_b64 s[56:57], s[58:59], s[56:57]
	v_cmp_gt_i32_e64 s[52:53], 17, v114
	s_and_b64 s[54:55], s[56:57], s[54:55]
	v_cmp_gt_i32_e64 s[50:51], 16, v114
	s_and_b64 s[52:53], s[54:55], s[52:53]
	v_cmp_gt_i32_e64 s[48:49], 11, v114
	s_and_b64 s[50:51], s[52:53], s[50:51]
	v_cmp_gt_i32_e64 s[46:47], 10, v114
	s_and_b64 s[48:49], s[50:51], s[48:49]
	v_cmp_gt_i32_e64 s[44:45], 9, v114
	s_and_b64 s[46:47], s[48:49], s[46:47]
	v_cmp_gt_i32_e64 s[42:43], 8, v114
	s_and_b64 s[44:45], s[46:47], s[44:45]
	v_cmp_gt_i32_e64 s[40:41], 3, v114
	s_and_b64 s[42:43], s[44:45], s[42:43]
	v_cmp_gt_i32_e64 s[38:39], 2, v114
	s_and_b64 s[40:41], s[42:43], s[40:41]
	v_cmp_gt_i32_e64 s[36:37], 1, v114
	s_and_b64 s[38:39], s[40:41], s[38:39]
	v_cmp_gt_i32_e64 s[34:35], 0, v114
	s_and_b64 s[36:37], s[38:39], s[36:37]
	s_and_b64 s[34:35], s[36:37], s[34:35]
	v_cmp_gt_i32_e64 s[28:29], 58, v114
	v_cndmask_b32_e64 v98, v98, v248, s[34:35]
	v_cmp_gt_i32_e64 s[34:35], 59, v114
	v_cmp_gt_i32_e64 s[26:27], 57, v114
	s_and_b64 s[28:29], s[34:35], s[28:29]
	v_cmp_gt_i32_e64 s[24:25], 56, v114
	s_and_b64 s[26:27], s[28:29], s[26:27]
	v_cmp_gt_i32_e64 s[22:23], 51, v114
	s_and_b64 s[24:25], s[26:27], s[24:25]
	v_cmp_gt_i32_e64 s[20:21], 50, v114
	s_and_b64 s[22:23], s[24:25], s[22:23]
	v_cmp_gt_i32_e64 s[18:19], 49, v114
	s_and_b64 s[20:21], s[22:23], s[20:21]
	v_cmp_gt_i32_e64 s[16:17], 48, v114
	s_and_b64 s[18:19], s[20:21], s[18:19]
	v_cmp_gt_i32_e64 s[14:15], 43, v114
	s_and_b64 s[16:17], s[18:19], s[16:17]
	v_cmp_gt_i32_e64 s[12:13], 42, v114
	s_and_b64 s[14:15], s[16:17], s[14:15]
	v_cmp_gt_i32_e64 s[10:11], 41, v114
	s_and_b64 s[12:13], s[14:15], s[12:13]
	v_cmp_gt_i32_e64 s[8:9], 40, v114
	s_and_b64 s[10:11], s[12:13], s[10:11]
	v_cmp_gt_i32_e64 s[6:7], 35, v114
	s_and_b64 s[8:9], s[10:11], s[8:9]
	v_cmp_gt_i32_e64 s[4:5], 34, v114
	s_and_b64 s[6:7], s[8:9], s[6:7]
	v_cmp_gt_i32_e64 s[2:3], 33, v114
	s_and_b64 s[4:5], s[6:7], s[4:5]
	v_cmp_gt_i32_e32 vcc, 32, v114
	s_and_b64 s[2:3], s[4:5], s[2:3]
	s_and_b64 vcc, s[2:3], vcc
	v_cndmask_b32_e64 v113, v113, v248, s[64:65]
	v_cndmask_b32_e64 v112, v112, v248, s[62:63]
	v_cndmask_b32_e64 v111, v111, v248, s[60:61]
	v_cndmask_b32_e64 v110, v110, v248, s[58:59]
	v_cndmask_b32_e64 v109, v109, v248, s[56:57]
	v_cndmask_b32_e64 v108, v108, v248, s[54:55]
	v_cndmask_b32_e64 v107, v107, v248, s[52:53]
	v_cndmask_b32_e64 v106, v106, v248, s[50:51]
	v_cndmask_b32_e64 v105, v105, v248, s[48:49]
	v_cndmask_b32_e64 v104, v104, v248, s[46:47]
	v_cndmask_b32_e64 v103, v103, v248, s[44:45]
	v_cndmask_b32_e64 v102, v102, v248, s[42:43]
	v_cndmask_b32_e64 v101, v101, v248, s[40:41]
	v_cndmask_b32_e64 v100, v100, v248, s[38:39]
	v_cndmask_b32_e64 v99, v99, v248, s[36:37]
	v_cndmask_b32_e64 v97, v97, v248, s[34:35]
	v_cndmask_b32_e64 v96, v96, v248, s[28:29]
	v_cndmask_b32_e64 v95, v95, v248, s[26:27]
	v_cndmask_b32_e64 v94, v94, v248, s[24:25]
	v_cndmask_b32_e64 v93, v93, v248, s[22:23]
	v_cndmask_b32_e64 v92, v92, v248, s[20:21]
	v_cndmask_b32_e64 v91, v91, v248, s[18:19]
	v_cndmask_b32_e64 v90, v90, v248, s[16:17]
	v_cndmask_b32_e64 v89, v89, v248, s[14:15]
	v_cndmask_b32_e64 v88, v88, v248, s[12:13]
	v_cndmask_b32_e64 v87, v87, v248, s[10:11]
	v_cndmask_b32_e64 v86, v86, v248, s[8:9]
	v_cndmask_b32_e64 v85, v85, v248, s[6:7]
	v_cndmask_b32_e64 v84, v84, v248, s[4:5]
	v_cndmask_b32_e64 v83, v83, v248, s[2:3]
	v_cndmask_b32_e32 v82, v82, v248, vcc

; __device__ __forceinline__ void cmask(f32x16&p0,f32x16&p1,int jb,int qrel,int hi){
;   const float NEG=-INFINITY; int d=qrel-64*jb-4*hi; asm volatile("":"+v"(d));
;   #pragma unroll
;   for(int r=0;r<16;++r){const int off=(r&3)+8*(r>>2); if(d<off)p0[r]=NEG; if(d<off+32)p1[r]=NEG;}
; }
.Lcm_empty_b:
	v_mov_b32_e32 v98, v248
	v_mov_b32_e32 v113, v248
	v_mov_b32_e32 v112, v248
	v_mov_b32_e32 v111, v248
	v_mov_b32_e32 v110, v248
	v_mov_b32_e32 v109, v248
	v_mov_b32_e32 v108, v248
	v_mov_b32_e32 v107, v248
	v_mov_b32_e32 v106, v248
	v_mov_b32_e32 v105, v248
	v_mov_b32_e32 v104, v248
	v_mov_b32_e32 v103, v248
	v_mov_b32_e32 v102, v248
	v_mov_b32_e32 v101, v248
	v_mov_b32_e32 v100, v248
	v_mov_b32_e32 v99, v248
	v_mov_b32_e32 v97, v248
	v_mov_b32_e32 v96, v248
	v_mov_b32_e32 v95, v248
	v_mov_b32_e32 v94, v248
	v_mov_b32_e32 v93, v248
	v_mov_b32_e32 v92, v248
	v_mov_b32_e32 v91, v248
	v_mov_b32_e32 v90, v248
	v_mov_b32_e32 v89, v248
	v_mov_b32_e32 v88, v248
	v_mov_b32_e32 v87, v248
	v_mov_b32_e32 v86, v248
	v_mov_b32_e32 v85, v248
	v_mov_b32_e32 v84, v248
	v_mov_b32_e32 v83, v248
	v_mov_b32_e32 v82, v248
	s_branch .LBB0_300
.Lcm_empty_a:
	v_mov_b32_e32 v130, v248
	v_mov_b32_e32 v145, v248
	v_mov_b32_e32 v144, v248
	v_mov_b32_e32 v143, v248
	v_mov_b32_e32 v142, v248
	v_mov_b32_e32 v141, v248
	v_mov_b32_e32 v140, v248
	v_mov_b32_e32 v139, v248
	v_mov_b32_e32 v138, v248
	v_mov_b32_e32 v137, v248
	v_mov_b32_e32 v136, v248
	v_mov_b32_e32 v135, v248
	v_mov_b32_e32 v134, v248
	v_mov_b32_e32 v133, v248
	v_mov_b32_e32 v132, v248
	v_mov_b32_e32 v131, v248
	v_mov_b32_e32 v129, v248
	v_mov_b32_e32 v128, v248
	v_mov_b32_e32 v127, v248
	v_mov_b32_e32 v126, v248
	v_mov_b32_e32 v125, v248
	v_mov_b32_e32 v124, v248
	v_mov_b32_e32 v123, v248
	v_mov_b32_e32 v122, v248
	v_mov_b32_e32 v121, v248
	v_mov_b32_e32 v120, v248
	v_mov_b32_e32 v119, v248
	v_mov_b32_e32 v118, v248
	v_mov_b32_e32 v117, v248
	v_mov_b32_e32 v116, v248
	v_mov_b32_e32 v115, v248
	v_mov_b32_e32 v114, v248
	s_branch .LBB0_286
